# EpiGate: -log2e folded into the per-row rstd scale (16 fewer v_mul per row group), on top of gelu+decay trims
# speedup vs baseline: 1.0102x; 1.0102x over previous
; __device__ __forceinline__ u32x4 pack8(f32x4 v0, f32x4 v1) { u32x4 w; w.x = cvt_pk_bf16(v0[0], v0[1]); w.y = cvt_pk_bf16(v0[2], v0[3]); w.z = cvt_pk_bf16(v1[0], v1[1]); w.w = cvt_pk_bf16(v1[2], v1[3]); return w; }
; __device__ __forceinline__ float sigm(float x) { return __builtin_amdgcn_rcpf(1.0f + __expf(-x)); }
;     __device__ __forceinline__ void operator()(f32x4 (&acc)[2][2][4][2], const Unit& u, int wr, int wc, int fr_, int fq_) const {
;     ...
;             for (int m = 0; m < 4; ++m) { const int row = row0 + ai * HALF + m * 16; const float rs = rstd[row]; bf16_t* rowp = GAB + (size_t)row * 4096 + col0;
; #pragma unroll
;                 for (int bj = 0; bj < 2; ++bj) { f32x4 v0 = acc[ai][bj][m][0] * rs, v1 = acc[ai][bj][m][1] * rs;
; #pragma unroll
;                     for (int i = 0; i < 4; ++i) { v0[i] = sigm(v0[i]); v1[i] = sigm(v1[i]); }
;                     *(u32x4*)(rowp + bj * HALF) = pack8(v0, v1); } }
.LBB0_1443:
	v_mov_b32_e32 v146, v150
	v_mov_b32_e32 v167, v151
	s_lshl_b32 s0, s0, 8
	s_add_i32 s0, s0, s69
	v_add_u32_e32 v146, s0, v146
	v_readlane_b32 s34, v244, 38
	v_ashrrev_i32_e32 v147, 31, v146
	v_readlane_b32 s35, v244, 39
	s_lshl_b32 s0, s1, 8
	s_or_b32 s0, s0, s70
	v_lshl_add_u64 v[148:149], v[146:147], 2, s[34:35]
	global_load_dword v168, v[148:149], off
	global_load_dword v245, v[148:149], off offset:64
	global_load_dword v246, v[148:149], off offset:128
	global_load_dword v247, v[148:149], off offset:192
	global_load_dword v248, v[148:149], off offset:512
	global_load_dword v249, v[148:149], off offset:576
	global_load_dword v250, v[148:149], off offset:640
	global_load_dword v251, v[148:149], off offset:704
	v_lshl_add_u32 v170, v167, 3, s0
	v_lshlrev_b64 v[146:147], 13, v[146:147]
	v_ashrrev_i32_e32 v171, 31, v170
	v_lshl_add_u64 v[146:147], s[26:27], 0, v[146:147]
	v_lshl_add_u64 v[146:147], v[170:171], 1, v[146:147]
	s_waitcnt vmcnt(0)
	v_mul_f32_e32 v168, 0xbfb8aa3b, v168
	v_pk_mul_f32 v[126:127], v[126:127], v[168:169] op_sel_hi:[1,0]
	v_pk_mul_f32 v[124:125], v[124:125], v[168:169] op_sel_hi:[1,0]
	v_pk_mul_f32 v[122:123], v[122:123], v[168:169] op_sel_hi:[1,0]
	v_pk_mul_f32 v[120:121], v[120:121], v[168:169] op_sel_hi:[1,0]
	v_pk_mul_f32 v[118:119], v[118:119], v[168:169] op_sel_hi:[1,0]
	v_pk_mul_f32 v[116:117], v[116:117], v[168:169] op_sel_hi:[1,0]
	v_pk_mul_f32 v[114:115], v[114:115], v[168:169] op_sel_hi:[1,0]
	v_pk_mul_f32 v[112:113], v[112:113], v[168:169] op_sel_hi:[1,0]
	v_exp_f32_e32 v124, v124
	v_exp_f32_e32 v120, v120
	v_exp_f32_e32 v125, v125
	v_exp_f32_e32 v121, v121
	v_exp_f32_e32 v126, v126
	v_exp_f32_e32 v122, v122
	v_exp_f32_e32 v127, v127
	v_exp_f32_e32 v123, v123
	v_exp_f32_e32 v116, v116
	v_exp_f32_e32 v112, v112
	v_exp_f32_e32 v117, v117
	v_exp_f32_e32 v113, v113
	v_exp_f32_e32 v118, v118
	v_exp_f32_e32 v114, v114
	v_exp_f32_e32 v119, v119
	v_exp_f32_e32 v115, v115
	v_add_f32_e32 v124, 1.0, v124
	v_add_f32_e32 v120, 1.0, v120
	v_add_f32_e32 v125, 1.0, v125
	v_add_f32_e32 v121, 1.0, v121
	v_add_f32_e32 v126, 1.0, v126
	v_add_f32_e32 v122, 1.0, v122
	v_add_f32_e32 v127, 1.0, v127
	v_add_f32_e32 v123, 1.0, v123
	v_add_f32_e32 v116, 1.0, v116
	v_add_f32_e32 v112, 1.0, v112
	v_add_f32_e32 v117, 1.0, v117
	v_add_f32_e32 v113, 1.0, v113
	v_add_f32_e32 v118, 1.0, v118
	v_add_f32_e32 v114, 1.0, v114
	v_add_f32_e32 v119, 1.0, v119
	v_add_f32_e32 v115, 1.0, v115
	v_rcp_f32_e32 v124, v124
	v_rcp_f32_e32 v120, v120
	v_rcp_f32_e32 v125, v125
	v_rcp_f32_e32 v121, v121
	v_rcp_f32_e32 v126, v126
	v_rcp_f32_e32 v122, v122
	v_rcp_f32_e32 v127, v127
	v_rcp_f32_e32 v123, v123
	v_rcp_f32_e32 v116, v116
	v_rcp_f32_e32 v167, v112
	v_rcp_f32_e32 v117, v117
	v_rcp_f32_e32 v168, v113
	v_rcp_f32_e32 v118, v118
	v_rcp_f32_e32 v169, v114
	v_rcp_f32_e32 v119, v119
	v_rcp_f32_e32 v170, v115
	v_cvt_pk_bf16_f32 v112, v124, v125
	v_cvt_pk_bf16_f32 v113, v126, v127
	v_cvt_pk_bf16_f32 v114, v120, v121
	v_cvt_pk_bf16_f32 v115, v122, v123
	v_cvt_pk_bf16_f32 v116, v116, v117
	v_cvt_pk_bf16_f32 v117, v118, v119
	v_cvt_pk_bf16_f32 v118, v167, v168
	v_cvt_pk_bf16_f32 v119, v169, v170
	global_store_dwordx4 v[146:147], v[112:115], off
	global_store_dwordx4 v[146:147], v[116:119], off offset:256
	s_nop 0
	v_lshl_add_u64 v[114:115], v[146:147], 0, s[16:17]
	v_add_co_u32_e32 v116, vcc, s76, v146
	v_mul_f32_e32 v112, 0xbfb8aa3b, v245
	v_pk_mul_f32 v[110:111], v[110:111], v[112:113] op_sel_hi:[1,0]
	v_pk_mul_f32 v[108:109], v[108:109], v[112:113] op_sel_hi:[1,0]
	v_pk_mul_f32 v[106:107], v[106:107], v[112:113] op_sel_hi:[1,0]
	v_pk_mul_f32 v[104:105], v[104:105], v[112:113] op_sel_hi:[1,0]
	v_pk_mul_f32 v[102:103], v[102:103], v[112:113] op_sel_hi:[1,0]
	v_pk_mul_f32 v[100:101], v[100:101], v[112:113] op_sel_hi:[1,0]
	v_pk_mul_f32 v[98:99], v[98:99], v[112:113] op_sel_hi:[1,0]
	v_pk_mul_f32 v[96:97], v[96:97], v[112:113] op_sel_hi:[1,0]
	v_exp_f32_e32 v108, v108
	v_exp_f32_e32 v104, v104
	v_exp_f32_e32 v109, v109
	v_exp_f32_e32 v105, v105
	v_exp_f32_e32 v110, v110
	v_exp_f32_e32 v106, v106
	v_exp_f32_e32 v111, v111
	v_exp_f32_e32 v107, v107
	v_exp_f32_e32 v100, v100
	v_exp_f32_e32 v96, v96
	v_exp_f32_e32 v101, v101
	v_exp_f32_e32 v97, v97
	v_exp_f32_e32 v102, v102
	v_exp_f32_e32 v98, v98
	v_exp_f32_e32 v103, v103
	v_exp_f32_e32 v99, v99
	v_add_f32_e32 v108, 1.0, v108
	v_add_f32_e32 v104, 1.0, v104
	v_add_f32_e32 v109, 1.0, v109
	v_add_f32_e32 v105, 1.0, v105
	v_add_f32_e32 v110, 1.0, v110
	v_add_f32_e32 v106, 1.0, v106
	v_add_f32_e32 v111, 1.0, v111
	v_add_f32_e32 v107, 1.0, v107
	v_add_f32_e32 v100, 1.0, v100
	v_add_f32_e32 v96, 1.0, v96
	v_add_f32_e32 v101, 1.0, v101
	v_add_f32_e32 v97, 1.0, v97
	v_add_f32_e32 v102, 1.0, v102
	v_add_f32_e32 v98, 1.0, v98
	v_add_f32_e32 v103, 1.0, v103
	v_add_f32_e32 v99, 1.0, v99
	v_rcp_f32_e32 v108, v108
	v_rcp_f32_e32 v104, v104
	v_rcp_f32_e32 v109, v109
	v_rcp_f32_e32 v105, v105
	v_rcp_f32_e32 v110, v110
	v_rcp_f32_e32 v106, v106
	v_rcp_f32_e32 v111, v111
	v_rcp_f32_e32 v107, v107
	v_rcp_f32_e32 v100, v100
	v_rcp_f32_e32 v112, v96
	v_rcp_f32_e32 v101, v101
	v_rcp_f32_e32 v113, v97
	v_rcp_f32_e32 v102, v102
	v_rcp_f32_e32 v118, v98
	v_rcp_f32_e32 v103, v103
	v_rcp_f32_e32 v119, v99
	v_addc_co_u32_e32 v117, vcc, 0, v147, vcc
	v_cvt_pk_bf16_f32 v96, v108, v109
	v_cvt_pk_bf16_f32 v97, v110, v111
	v_cvt_pk_bf16_f32 v98, v104, v105
	v_cvt_pk_bf16_f32 v99, v106, v107
	v_cvt_pk_bf16_f32 v100, v100, v101
	v_cvt_pk_bf16_f32 v101, v102, v103
	v_cvt_pk_bf16_f32 v102, v112, v113
	v_cvt_pk_bf16_f32 v103, v118, v119
	global_store_dwordx4 v[116:117], v[96:99], off
	global_store_dwordx4 v[114:115], v[100:103], off offset:256
; __device__ __forceinline__ unsigned cvt_pk_bf16(float lo, float hi) { const cvt_f32x2_t v = {lo, hi}; const cvt_bf16x2_t b = __builtin_convertvector(v, cvt_bf16x2_t); return __builtin_bit_cast(unsigned, b); }
; __device__ __forceinline__ float bf2f(unsigned short h) { return __uint_as_float(((unsigned)h) << 16); }
; __device__ __forceinline__ float sigm(float x) { return __builtin_amdgcn_rcpf(1.0f + __expf(-x)); }
; __device__ __forceinline__ float bf2f(unsigned short h) { return __uint_as_float(((unsigned)h) << 16); }
; __device__ __forceinline__ u32x4 pack8(f32x4 v0, f32x4 v1) { u32x4 w; w.x = cvt_pk_bf16(v0[0], v0[1]); w.y = cvt_pk_bf16(v0[2], v0[3]); w.z = cvt_pk_bf16(v1[0], v1[1]); w.w = cvt_pk_bf16(v1[2], v1[3]); return w; }
;     __device__ __forceinline__ void operator()(f32x4 (&acc)[2][2][4][2], const Unit& u, int wr, int wc, int fr_, int fq_) const {
;     ...
;             for (int m = 0; m < 4; ++m) { const int row = row0 + ai * HALF + m * 16; const float rs = rstd[row]; bf16_t* rowp = GAB + (size_t)row * 4096 + col0;
; #pragma unroll
;                 for (int bj = 0; bj < 2; ++bj) { f32x4 v0 = acc[ai][bj][m][0] * rs, v1 = acc[ai][bj][m][1] * rs;
; #pragma unroll
;                     for (int i = 0; i < 4; ++i) { v0[i] = sigm(v0[i]); v1[i] = sigm(v1[i]); }
;                     *(u32x4*)(rowp + bj * HALF) = pack8(v0, v1); } }
	s_nop 0
	v_lshl_add_u64 v[98:99], v[146:147], 0, s[18:19]
	v_add_co_u32_e32 v100, vcc, s77, v146
	v_mul_f32_e32 v96, 0xbfb8aa3b, v246
	v_pk_mul_f32 v[94:95], v[94:95], v[96:97] op_sel_hi:[1,0]
	v_pk_mul_f32 v[92:93], v[92:93], v[96:97] op_sel_hi:[1,0]
	v_pk_mul_f32 v[90:91], v[90:91], v[96:97] op_sel_hi:[1,0]
	v_pk_mul_f32 v[88:89], v[88:89], v[96:97] op_sel_hi:[1,0]
	v_pk_mul_f32 v[86:87], v[86:87], v[96:97] op_sel_hi:[1,0]
	v_pk_mul_f32 v[84:85], v[84:85], v[96:97] op_sel_hi:[1,0]
	v_pk_mul_f32 v[82:83], v[82:83], v[96:97] op_sel_hi:[1,0]
	v_pk_mul_f32 v[80:81], v[80:81], v[96:97] op_sel_hi:[1,0]
	v_exp_f32_e32 v92, v92
	v_exp_f32_e32 v88, v88
	v_exp_f32_e32 v93, v93
	v_exp_f32_e32 v89, v89
	v_exp_f32_e32 v94, v94
	v_exp_f32_e32 v90, v90
	v_exp_f32_e32 v95, v95
	v_exp_f32_e32 v91, v91
	v_exp_f32_e32 v84, v84
	v_exp_f32_e32 v80, v80
	v_exp_f32_e32 v85, v85
	v_exp_f32_e32 v81, v81
	v_exp_f32_e32 v86, v86
	v_exp_f32_e32 v82, v82
	v_exp_f32_e32 v87, v87
	v_exp_f32_e32 v83, v83
	v_add_f32_e32 v92, 1.0, v92
	v_add_f32_e32 v88, 1.0, v88
	v_add_f32_e32 v93, 1.0, v93
	v_add_f32_e32 v89, 1.0, v89
	v_add_f32_e32 v94, 1.0, v94
	v_add_f32_e32 v90, 1.0, v90
	v_add_f32_e32 v95, 1.0, v95
	v_add_f32_e32 v91, 1.0, v91
	v_add_f32_e32 v84, 1.0, v84
	v_add_f32_e32 v80, 1.0, v80
	v_add_f32_e32 v85, 1.0, v85
	v_add_f32_e32 v81, 1.0, v81
	v_add_f32_e32 v86, 1.0, v86
	v_add_f32_e32 v82, 1.0, v82
	v_add_f32_e32 v87, 1.0, v87
	v_add_f32_e32 v83, 1.0, v83
	v_rcp_f32_e32 v92, v92
	v_rcp_f32_e32 v88, v88
	v_rcp_f32_e32 v93, v93
	v_rcp_f32_e32 v89, v89
	v_rcp_f32_e32 v94, v94
	v_rcp_f32_e32 v90, v90
	v_rcp_f32_e32 v95, v95
	v_rcp_f32_e32 v91, v91
	v_rcp_f32_e32 v84, v84
	v_rcp_f32_e32 v96, v80
	v_rcp_f32_e32 v85, v85
	v_rcp_f32_e32 v97, v81
	v_rcp_f32_e32 v86, v86
	v_rcp_f32_e32 v102, v82
	v_rcp_f32_e32 v87, v87
	v_rcp_f32_e32 v103, v83
	v_addc_co_u32_e32 v101, vcc, 0, v147, vcc
	v_cvt_pk_bf16_f32 v80, v92, v93
	v_cvt_pk_bf16_f32 v81, v94, v95
	v_cvt_pk_bf16_f32 v82, v88, v89
	v_cvt_pk_bf16_f32 v83, v90, v91
	v_cvt_pk_bf16_f32 v84, v84, v85
	v_cvt_pk_bf16_f32 v85, v86, v87
	v_cvt_pk_bf16_f32 v86, v96, v97
	v_cvt_pk_bf16_f32 v87, v102, v103
	global_store_dwordx4 v[100:101], v[80:83], off
	global_store_dwordx4 v[98:99], v[84:87], off offset:256
	s_nop 0
	v_lshl_add_u64 v[82:83], v[146:147], 0, s[22:23]
	v_add_co_u32_e32 v84, vcc, s78, v146
	v_mul_f32_e32 v80, 0xbfb8aa3b, v247
	v_pk_mul_f32 v[78:79], v[78:79], v[80:81] op_sel_hi:[1,0]
	v_pk_mul_f32 v[76:77], v[76:77], v[80:81] op_sel_hi:[1,0]
	v_pk_mul_f32 v[74:75], v[74:75], v[80:81] op_sel_hi:[1,0]
	v_pk_mul_f32 v[72:73], v[72:73], v[80:81] op_sel_hi:[1,0]
	v_pk_mul_f32 v[70:71], v[70:71], v[80:81] op_sel_hi:[1,0]
	v_pk_mul_f32 v[68:69], v[68:69], v[80:81] op_sel_hi:[1,0]
	v_pk_mul_f32 v[66:67], v[66:67], v[80:81] op_sel_hi:[1,0]
	v_pk_mul_f32 v[64:65], v[64:65], v[80:81] op_sel_hi:[1,0]
	v_exp_f32_e32 v76, v76
	v_exp_f32_e32 v72, v72
	v_exp_f32_e32 v77, v77
	v_exp_f32_e32 v73, v73
	v_exp_f32_e32 v78, v78
	v_exp_f32_e32 v74, v74
	v_exp_f32_e32 v79, v79
	v_exp_f32_e32 v75, v75
	v_exp_f32_e32 v68, v68
	v_exp_f32_e32 v64, v64
	v_exp_f32_e32 v69, v69
	v_exp_f32_e32 v65, v65
	v_exp_f32_e32 v70, v70
	v_exp_f32_e32 v66, v66
	v_exp_f32_e32 v71, v71
	v_exp_f32_e32 v67, v67
	v_add_f32_e32 v76, 1.0, v76
	v_add_f32_e32 v72, 1.0, v72
	v_add_f32_e32 v77, 1.0, v77
	v_add_f32_e32 v73, 1.0, v73
	v_add_f32_e32 v78, 1.0, v78
	v_add_f32_e32 v74, 1.0, v74
	v_add_f32_e32 v79, 1.0, v79
	v_add_f32_e32 v75, 1.0, v75
	v_add_f32_e32 v68, 1.0, v68
	v_add_f32_e32 v64, 1.0, v64
	v_add_f32_e32 v69, 1.0, v69
	v_add_f32_e32 v65, 1.0, v65
	v_add_f32_e32 v70, 1.0, v70
	v_add_f32_e32 v66, 1.0, v66
	v_add_f32_e32 v71, 1.0, v71
	v_add_f32_e32 v67, 1.0, v67
	v_rcp_f32_e32 v76, v76
	v_rcp_f32_e32 v72, v72
	v_rcp_f32_e32 v77, v77
	v_rcp_f32_e32 v73, v73
	v_rcp_f32_e32 v78, v78
	v_rcp_f32_e32 v74, v74
	v_rcp_f32_e32 v79, v79
	v_rcp_f32_e32 v75, v75
	v_rcp_f32_e32 v68, v68
	v_rcp_f32_e32 v80, v64
	v_rcp_f32_e32 v69, v69
	v_rcp_f32_e32 v81, v65
	v_rcp_f32_e32 v70, v70
	v_rcp_f32_e32 v86, v66
	v_rcp_f32_e32 v71, v71
	v_rcp_f32_e32 v87, v67
	v_addc_co_u32_e32 v85, vcc, 0, v147, vcc
	v_cvt_pk_bf16_f32 v64, v76, v77
	v_cvt_pk_bf16_f32 v65, v78, v79
	v_cvt_pk_bf16_f32 v66, v72, v73
	v_cvt_pk_bf16_f32 v67, v74, v75
	v_cvt_pk_bf16_f32 v68, v68, v69
	v_cvt_pk_bf16_f32 v69, v70, v71
	v_cvt_pk_bf16_f32 v70, v80, v81
	v_cvt_pk_bf16_f32 v71, v86, v87
	global_store_dwordx4 v[84:85], v[64:67], off
	global_store_dwordx4 v[82:83], v[68:71], off offset:256
	s_nop 0
	v_lshl_add_u64 v[66:67], v[146:147], 0, s[36:37]
	v_add_co_u32_e32 v68, vcc, s79, v146
	v_mul_f32_e32 v64, 0xbfb8aa3b, v248
	v_pk_mul_f32 v[62:63], v[62:63], v[64:65] op_sel_hi:[1,0]
	v_pk_mul_f32 v[60:61], v[60:61], v[64:65] op_sel_hi:[1,0]
	v_pk_mul_f32 v[58:59], v[58:59], v[64:65] op_sel_hi:[1,0]
	v_pk_mul_f32 v[56:57], v[56:57], v[64:65] op_sel_hi:[1,0]
	v_pk_mul_f32 v[54:55], v[54:55], v[64:65] op_sel_hi:[1,0]
	v_pk_mul_f32 v[52:53], v[52:53], v[64:65] op_sel_hi:[1,0]
	v_pk_mul_f32 v[50:51], v[50:51], v[64:65] op_sel_hi:[1,0]
	v_pk_mul_f32 v[48:49], v[48:49], v[64:65] op_sel_hi:[1,0]
	v_exp_f32_e32 v60, v60
	v_exp_f32_e32 v56, v56
	v_exp_f32_e32 v61, v61
	v_exp_f32_e32 v57, v57
	v_exp_f32_e32 v62, v62
	v_exp_f32_e32 v58, v58
	v_exp_f32_e32 v63, v63
	v_exp_f32_e32 v59, v59
	v_exp_f32_e32 v52, v52
	v_exp_f32_e32 v48, v48
	v_exp_f32_e32 v53, v53
	v_exp_f32_e32 v49, v49
	v_exp_f32_e32 v54, v54
	v_exp_f32_e32 v50, v50
	v_exp_f32_e32 v55, v55
	v_exp_f32_e32 v51, v51
	v_add_f32_e32 v60, 1.0, v60
	v_add_f32_e32 v56, 1.0, v56
	v_add_f32_e32 v61, 1.0, v61
	v_add_f32_e32 v57, 1.0, v57
	v_add_f32_e32 v62, 1.0, v62
; __device__ __forceinline__ unsigned cvt_pk_bf16(float lo, float hi) { const cvt_f32x2_t v = {lo, hi}; const cvt_bf16x2_t b = __builtin_convertvector(v, cvt_bf16x2_t); return __builtin_bit_cast(unsigned, b); }
; __device__ __forceinline__ float bf2f(unsigned short h) { return __uint_as_float(((unsigned)h) << 16); }
; __device__ __forceinline__ float sigm(float x) { return __builtin_amdgcn_rcpf(1.0f + __expf(-x)); }
; __device__ __forceinline__ float bf2f(unsigned short h) { return __uint_as_float(((unsigned)h) << 16); }
; __device__ __forceinline__ u32x4 pack8(f32x4 v0, f32x4 v1) { u32x4 w; w.x = cvt_pk_bf16(v0[0], v0[1]); w.y = cvt_pk_bf16(v0[2], v0[3]); w.z = cvt_pk_bf16(v1[0], v1[1]); w.w = cvt_pk_bf16(v1[2], v1[3]); return w; }
;     __device__ __forceinline__ void operator()(f32x4 (&acc)[2][2][4][2], const Unit& u, int wr, int wc, int fr_, int fq_) const {
;     ...
;             for (int m = 0; m < 4; ++m) { const int row = row0 + ai * HALF + m * 16; const float rs = rstd[row]; bf16_t* rowp = GAB + (size_t)row * 4096 + col0;
; #pragma unroll
;                 for (int bj = 0; bj < 2; ++bj) { f32x4 v0 = acc[ai][bj][m][0] * rs, v1 = acc[ai][bj][m][1] * rs;
; #pragma unroll
;                     for (int i = 0; i < 4; ++i) { v0[i] = sigm(v0[i]); v1[i] = sigm(v1[i]); }
;                     *(u32x4*)(rowp + bj * HALF) = pack8(v0, v1); } }
	v_add_f32_e32 v58, 1.0, v58
	v_add_f32_e32 v63, 1.0, v63
	v_add_f32_e32 v59, 1.0, v59
	v_add_f32_e32 v52, 1.0, v52
	v_add_f32_e32 v48, 1.0, v48
	v_add_f32_e32 v53, 1.0, v53
	v_add_f32_e32 v49, 1.0, v49
	v_add_f32_e32 v54, 1.0, v54
	v_add_f32_e32 v50, 1.0, v50
	v_add_f32_e32 v55, 1.0, v55
	v_add_f32_e32 v51, 1.0, v51
	v_rcp_f32_e32 v60, v60
	v_rcp_f32_e32 v56, v56
	v_rcp_f32_e32 v61, v61
	v_rcp_f32_e32 v57, v57
	v_rcp_f32_e32 v62, v62
	v_rcp_f32_e32 v58, v58
	v_rcp_f32_e32 v63, v63
	v_rcp_f32_e32 v59, v59
	v_rcp_f32_e32 v52, v52
	v_rcp_f32_e32 v64, v48
	v_rcp_f32_e32 v53, v53
	v_rcp_f32_e32 v65, v49
	v_rcp_f32_e32 v54, v54
	v_rcp_f32_e32 v70, v50
	v_rcp_f32_e32 v55, v55
	v_rcp_f32_e32 v71, v51
	v_addc_co_u32_e32 v69, vcc, 0, v147, vcc
	v_cvt_pk_bf16_f32 v48, v60, v61
	v_cvt_pk_bf16_f32 v49, v62, v63
	v_cvt_pk_bf16_f32 v50, v56, v57
	v_cvt_pk_bf16_f32 v51, v58, v59
	v_cvt_pk_bf16_f32 v52, v52, v53
	v_cvt_pk_bf16_f32 v53, v54, v55
	v_cvt_pk_bf16_f32 v54, v64, v65
	v_cvt_pk_bf16_f32 v55, v70, v71
	global_store_dwordx4 v[68:69], v[48:51], off
	global_store_dwordx4 v[66:67], v[52:55], off offset:256
	s_nop 0
	v_lshl_add_u64 v[50:51], v[146:147], 0, s[38:39]
	v_add_co_u32_e32 v52, vcc, s80, v146
	v_mul_f32_e32 v48, 0xbfb8aa3b, v249
	v_pk_mul_f32 v[46:47], v[46:47], v[48:49] op_sel_hi:[1,0]
	v_pk_mul_f32 v[44:45], v[44:45], v[48:49] op_sel_hi:[1,0]
	v_pk_mul_f32 v[42:43], v[42:43], v[48:49] op_sel_hi:[1,0]
	v_pk_mul_f32 v[40:41], v[40:41], v[48:49] op_sel_hi:[1,0]
	v_pk_mul_f32 v[38:39], v[38:39], v[48:49] op_sel_hi:[1,0]
	v_pk_mul_f32 v[36:37], v[36:37], v[48:49] op_sel_hi:[1,0]
	v_pk_mul_f32 v[34:35], v[34:35], v[48:49] op_sel_hi:[1,0]
	v_pk_mul_f32 v[32:33], v[32:33], v[48:49] op_sel_hi:[1,0]
	v_exp_f32_e32 v44, v44
	v_exp_f32_e32 v40, v40
	v_exp_f32_e32 v45, v45
	v_exp_f32_e32 v41, v41
	v_exp_f32_e32 v46, v46
	v_exp_f32_e32 v42, v42
	v_exp_f32_e32 v47, v47
	v_exp_f32_e32 v43, v43
	v_exp_f32_e32 v36, v36
	v_exp_f32_e32 v32, v32
	v_exp_f32_e32 v37, v37
	v_exp_f32_e32 v33, v33
	v_exp_f32_e32 v38, v38
	v_exp_f32_e32 v34, v34
	v_exp_f32_e32 v39, v39
	v_exp_f32_e32 v35, v35
	v_add_f32_e32 v44, 1.0, v44
	v_add_f32_e32 v40, 1.0, v40
	v_add_f32_e32 v45, 1.0, v45
	v_add_f32_e32 v41, 1.0, v41
	v_add_f32_e32 v46, 1.0, v46
	v_add_f32_e32 v42, 1.0, v42
	v_add_f32_e32 v47, 1.0, v47
	v_add_f32_e32 v43, 1.0, v43
	v_add_f32_e32 v36, 1.0, v36
	v_add_f32_e32 v32, 1.0, v32
	v_add_f32_e32 v37, 1.0, v37
	v_add_f32_e32 v33, 1.0, v33
	v_add_f32_e32 v38, 1.0, v38
	v_add_f32_e32 v34, 1.0, v34
	v_add_f32_e32 v39, 1.0, v39
	v_add_f32_e32 v35, 1.0, v35
	v_rcp_f32_e32 v44, v44
	v_rcp_f32_e32 v40, v40
	v_rcp_f32_e32 v45, v45
	v_rcp_f32_e32 v41, v41
	v_rcp_f32_e32 v46, v46
	v_rcp_f32_e32 v42, v42
	v_rcp_f32_e32 v47, v47
	v_rcp_f32_e32 v43, v43
	v_rcp_f32_e32 v36, v36
	v_rcp_f32_e32 v48, v32
	v_rcp_f32_e32 v37, v37
	v_rcp_f32_e32 v49, v33
	v_rcp_f32_e32 v38, v38
	v_rcp_f32_e32 v54, v34
	v_rcp_f32_e32 v39, v39
	v_rcp_f32_e32 v55, v35
	v_addc_co_u32_e32 v53, vcc, 0, v147, vcc
	v_cvt_pk_bf16_f32 v32, v44, v45
	v_cvt_pk_bf16_f32 v33, v46, v47
	v_cvt_pk_bf16_f32 v34, v40, v41
	v_cvt_pk_bf16_f32 v35, v42, v43
	v_cvt_pk_bf16_f32 v36, v36, v37
	v_cvt_pk_bf16_f32 v37, v38, v39
	v_cvt_pk_bf16_f32 v38, v48, v49
	v_cvt_pk_bf16_f32 v39, v54, v55
	global_store_dwordx4 v[52:53], v[32:35], off
	global_store_dwordx4 v[50:51], v[36:39], off offset:256
	s_nop 0
	v_lshl_add_u64 v[34:35], v[146:147], 0, s[40:41]
	v_add_co_u32_e32 v36, vcc, s81, v146
	v_mul_f32_e32 v32, 0xbfb8aa3b, v250
	v_pk_mul_f32 v[30:31], v[30:31], v[32:33] op_sel_hi:[1,0]
	v_pk_mul_f32 v[28:29], v[28:29], v[32:33] op_sel_hi:[1,0]
	v_pk_mul_f32 v[26:27], v[26:27], v[32:33] op_sel_hi:[1,0]
	v_pk_mul_f32 v[24:25], v[24:25], v[32:33] op_sel_hi:[1,0]
	v_pk_mul_f32 v[22:23], v[22:23], v[32:33] op_sel_hi:[1,0]
	v_pk_mul_f32 v[20:21], v[20:21], v[32:33] op_sel_hi:[1,0]
	v_pk_mul_f32 v[18:19], v[18:19], v[32:33] op_sel_hi:[1,0]
	v_pk_mul_f32 v[16:17], v[16:17], v[32:33] op_sel_hi:[1,0]
; __device__ __forceinline__ unsigned cvt_pk_bf16(float lo, float hi) { const cvt_f32x2_t v = {lo, hi}; const cvt_bf16x2_t b = __builtin_convertvector(v, cvt_bf16x2_t); return __builtin_bit_cast(unsigned, b); }
; __device__ __forceinline__ float bf2f(unsigned short h) { return __uint_as_float(((unsigned)h) << 16); }
; __device__ __forceinline__ float sigm(float x) { return __builtin_amdgcn_rcpf(1.0f + __expf(-x)); }
; __device__ __forceinline__ float bf2f(unsigned short h) { return __uint_as_float(((unsigned)h) << 16); }
; __device__ __forceinline__ u32x4 pack8(f32x4 v0, f32x4 v1) { u32x4 w; w.x = cvt_pk_bf16(v0[0], v0[1]); w.y = cvt_pk_bf16(v0[2], v0[3]); w.z = cvt_pk_bf16(v1[0], v1[1]); w.w = cvt_pk_bf16(v1[2], v1[3]); return w; }
;     __device__ __forceinline__ void operator()(f32x4 (&acc)[2][2][4][2], const Unit& u, int wr, int wc, int fr_, int fq_) const {
;     ...
;             for (int m = 0; m < 4; ++m) { const int row = row0 + ai * HALF + m * 16; const float rs = rstd[row]; bf16_t* rowp = GAB + (size_t)row * 4096 + col0;
; #pragma unroll
;                 for (int bj = 0; bj < 2; ++bj) { f32x4 v0 = acc[ai][bj][m][0] * rs, v1 = acc[ai][bj][m][1] * rs;
; #pragma unroll
;                     for (int i = 0; i < 4; ++i) { v0[i] = sigm(v0[i]); v1[i] = sigm(v1[i]); }
;                     *(u32x4*)(rowp + bj * HALF) = pack8(v0, v1); } }
	v_exp_f32_e32 v28, v28
	v_exp_f32_e32 v24, v24
	v_exp_f32_e32 v29, v29
	v_exp_f32_e32 v25, v25
	v_exp_f32_e32 v30, v30
	v_exp_f32_e32 v26, v26
	v_exp_f32_e32 v31, v31
	v_exp_f32_e32 v27, v27
	v_exp_f32_e32 v20, v20
	v_exp_f32_e32 v16, v16
	v_exp_f32_e32 v21, v21
	v_exp_f32_e32 v17, v17
	v_exp_f32_e32 v22, v22
	v_exp_f32_e32 v18, v18
	v_exp_f32_e32 v23, v23
	v_exp_f32_e32 v19, v19
	v_add_f32_e32 v28, 1.0, v28
	v_add_f32_e32 v24, 1.0, v24
	v_add_f32_e32 v29, 1.0, v29
	v_add_f32_e32 v25, 1.0, v25
	v_add_f32_e32 v30, 1.0, v30
	v_add_f32_e32 v26, 1.0, v26
	v_add_f32_e32 v31, 1.0, v31
	v_add_f32_e32 v27, 1.0, v27
	v_add_f32_e32 v20, 1.0, v20
	v_add_f32_e32 v16, 1.0, v16
	v_add_f32_e32 v21, 1.0, v21
	v_add_f32_e32 v17, 1.0, v17
	v_add_f32_e32 v22, 1.0, v22
	v_add_f32_e32 v18, 1.0, v18
	v_add_f32_e32 v23, 1.0, v23
	v_add_f32_e32 v19, 1.0, v19
	v_rcp_f32_e32 v28, v28
	v_rcp_f32_e32 v24, v24
	v_rcp_f32_e32 v29, v29
	v_rcp_f32_e32 v25, v25
	v_rcp_f32_e32 v30, v30
	v_rcp_f32_e32 v26, v26
	v_rcp_f32_e32 v31, v31
	v_rcp_f32_e32 v27, v27
	v_rcp_f32_e32 v20, v20
	v_rcp_f32_e32 v32, v16
	v_rcp_f32_e32 v21, v21
	v_rcp_f32_e32 v33, v17
	v_rcp_f32_e32 v22, v22
	v_rcp_f32_e32 v38, v18
	v_rcp_f32_e32 v23, v23
	v_rcp_f32_e32 v39, v19
	v_addc_co_u32_e32 v37, vcc, 0, v147, vcc
	v_cvt_pk_bf16_f32 v16, v28, v29
	v_cvt_pk_bf16_f32 v17, v30, v31
	v_cvt_pk_bf16_f32 v18, v24, v25
	v_cvt_pk_bf16_f32 v19, v26, v27
	v_cvt_pk_bf16_f32 v20, v20, v21
	v_cvt_pk_bf16_f32 v21, v22, v23
	v_cvt_pk_bf16_f32 v22, v32, v33
	v_cvt_pk_bf16_f32 v23, v38, v39
	global_store_dwordx4 v[36:37], v[16:19], off
	global_store_dwordx4 v[34:35], v[20:23], off offset:256
	s_nop 0
	s_andn2_b64 vcc, exec, s[4:5]
	v_add_co_u32_e64 v20, s[0:1], s82, v146
	v_lshl_add_u64 v[18:19], v[146:147], 0, s[42:43]
	s_nop 0
	v_addc_co_u32_e64 v21, s[0:1], 0, v147, s[0:1]
	s_mov_b64 s[0:1], -1
	v_mul_f32_e32 v16, 0xbfb8aa3b, v251
	v_pk_mul_f32 v[14:15], v[14:15], v[16:17] op_sel_hi:[1,0]
	v_pk_mul_f32 v[12:13], v[12:13], v[16:17] op_sel_hi:[1,0]
	v_pk_mul_f32 v[10:11], v[10:11], v[16:17] op_sel_hi:[1,0]
	v_pk_mul_f32 v[8:9], v[8:9], v[16:17] op_sel_hi:[1,0]
	v_pk_mul_f32 v[6:7], v[6:7], v[16:17] op_sel_hi:[1,0]
	v_pk_mul_f32 v[4:5], v[4:5], v[16:17] op_sel_hi:[1,0]
	v_pk_mul_f32 v[2:3], v[2:3], v[16:17] op_sel_hi:[1,0]
	v_pk_mul_f32 v[0:1], v[0:1], v[16:17] op_sel_hi:[1,0]
	v_exp_f32_e32 v12, v12
	v_exp_f32_e32 v8, v8
	v_exp_f32_e32 v13, v13
	v_exp_f32_e32 v9, v9
	v_exp_f32_e32 v14, v14
	v_exp_f32_e32 v10, v10
	v_exp_f32_e32 v15, v15
	v_exp_f32_e32 v11, v11
	v_exp_f32_e32 v4, v4
	v_exp_f32_e32 v0, v0
	v_exp_f32_e32 v5, v5
	v_exp_f32_e32 v1, v1
	v_exp_f32_e32 v6, v6
	v_exp_f32_e32 v2, v2
	v_exp_f32_e32 v7, v7
	v_exp_f32_e32 v3, v3
	v_add_f32_e32 v12, 1.0, v12
	v_add_f32_e32 v8, 1.0, v8
	v_add_f32_e32 v13, 1.0, v13
	v_add_f32_e32 v9, 1.0, v9
	v_add_f32_e32 v14, 1.0, v14
	v_add_f32_e32 v10, 1.0, v10
	v_add_f32_e32 v15, 1.0, v15
	v_add_f32_e32 v11, 1.0, v11
	v_add_f32_e32 v4, 1.0, v4
	v_add_f32_e32 v0, 1.0, v0
	v_add_f32_e32 v5, 1.0, v5
	v_add_f32_e32 v1, 1.0, v1
	v_add_f32_e32 v6, 1.0, v6
	v_add_f32_e32 v2, 1.0, v2
	v_add_f32_e32 v7, 1.0, v7
	v_add_f32_e32 v3, 1.0, v3
	v_rcp_f32_e32 v12, v12
	v_rcp_f32_e32 v8, v8
	v_rcp_f32_e32 v13, v13
	v_rcp_f32_e32 v9, v9
	v_rcp_f32_e32 v14, v14
	v_rcp_f32_e32 v10, v10
	v_rcp_f32_e32 v15, v15
	v_rcp_f32_e32 v11, v11
	v_rcp_f32_e32 v4, v4
	v_rcp_f32_e32 v16, v0
	v_rcp_f32_e32 v5, v5
	v_rcp_f32_e32 v17, v1
	v_rcp_f32_e32 v6, v6
	v_rcp_f32_e32 v22, v2
	v_rcp_f32_e32 v7, v7
	v_rcp_f32_e32 v23, v3
	v_cvt_pk_bf16_f32 v0, v12, v13
	v_cvt_pk_bf16_f32 v1, v14, v15
	v_cvt_pk_bf16_f32 v2, v8, v9
	v_cvt_pk_bf16_f32 v3, v10, v11
	v_cvt_pk_bf16_f32 v4, v4, v5
	v_cvt_pk_bf16_f32 v5, v6, v7
	v_cvt_pk_bf16_f32 v6, v16, v17
	v_cvt_pk_bf16_f32 v7, v22, v23
	global_store_dwordx4 v[20:21], v[0:3], off
	global_store_dwordx4 v[18:19], v[4:7], off offset:256
	s_cbranch_vccnz .LBB0_1432
	s_andn2_b64 vcc, exec, s[10:11]
	s_cbranch_vccnz .LBB0_1431
	s_barrier
	s_branch .LBB0_1431
